# EpiRes epilogue preamble: gate/scale/gain loads and first residual batch issued back to back with one wait
# speedup vs baseline: 1.0280x; 1.0009x over previous
.LBB0_772:
	s_min_i32 s8, s54, 0x80
	s_ashr_i32 s8, s8, 3
	v_lshl_or_b32 v128, s17, 8, v229
	s_mul_i32 s41, s8, 0x9000
	s_mul_hi_i32 s40, s8, 0x9000
	s_add_u32 s8, s76, s41
	v_ashrrev_i32_e32 v129, 31, v128
	s_addc_u32 s9, s77, s40
	v_lshlrev_b64 v[134:135], 2, v[128:129]
	v_lshl_add_u64 v[132:133], s[8:9], 0, v[134:135]
	flat_load_dwordx4 v[144:147], v[132:133]
	s_add_u32 s8, s78, s41
	s_addc_u32 s9, s79, s40
	v_cndmask_b32_e64 v129, 0, 1, s[28:29]
	v_lshl_add_u64 v[130:131], s[48:49], 0, v[134:135]
	v_lshl_add_u64 v[134:135], s[8:9], 0, v[134:135]
	v_cmp_ne_u32_e64 s[8:9], 1, v129
	flat_load_dwordx4 v[156:159], v[132:133] offset:16
	flat_load_dwordx4 v[160:163], v[132:133] offset:512
	flat_load_dwordx4 v[164:167], v[132:133] offset:528
	s_andn2_b64 vcc, exec, s[28:29]
	s_cbranch_vccnz .Lres_pre_skip_c0
	flat_load_dwordx4 v[186:189], v[134:135]
	flat_load_dwordx4 v[238:241], v[130:131]
	flat_load_dwordx4 v[190:193], v[134:135] offset:16
	flat_load_dwordx4 v[242:245], v[130:131] offset:16
	flat_load_dwordx4 v[194:197], v[134:135] offset:512
	flat_load_dwordx4 v[246:249], v[130:131] offset:512
	flat_load_dwordx4 v[198:201], v[134:135] offset:528
	flat_load_dwordx4 v[250:253], v[130:131] offset:528
.Lres_pre_skip_c0:
	s_lshl_b32 s40, s54, 8
	s_add_i32 s44, s40, 0xffff8000
	s_ashr_i32 s41, s40, 31
	s_lshl_b64 s[50:51], s[44:45], 12
	s_add_u32 s52, s14, s50
	s_addc_u32 s53, s15, s51
	s_lshl_b64 s[50:51], s[40:41], 12
	s_add_u32 s55, s10, s50
	s_addc_u32 s64, s11, s51
	s_cmpk_lt_i32 s54, 0x80
	s_cselect_b32 s51, s41, 0
	s_cselect_b32 s50, s40, s44
	s_cselect_b32 s44, s21, s47
	s_cselect_b32 s65, s20, s46
	s_cselect_b32 s54, s40, s40
	s_cselect_b32 s41, s64, s53
	s_cselect_b32 s40, s55, s52
	s_lshl_b64 s[52:53], s[50:51], 12
	s_add_u32 s52, s65, s52
	v_add_u32_e32 v176, v230, v128
	s_addc_u32 s53, s44, s53
	v_lshlrev_b64 v[178:179], 2, v[176:177]
	v_lshl_add_u64 v[210:211], s[52:53], 0, v[178:179]
	s_mov_b32 s44, 0x10000
	s_mov_b64 s[52:53], 0x10000
	v_add_co_u32_e32 v130, vcc, s44, v210
	v_lshl_add_u64 v[128:129], v[210:211], 0, s[52:53]
	s_nop 0
	v_addc_co_u32_e32 v131, vcc, 0, v211, vcc
	s_mov_b64 s[52:53], 0x10200
	global_load_dwordx4 v[220:223], v[210:211], off offset:16 nt
	global_load_dwordx4 v[232:235], v[210:211], off nt
	global_load_dwordx4 v[148:151], v[210:211], off offset:528 nt
	global_load_dwordx4 v[152:155], v[210:211], off offset:512 nt
	global_load_dwordx4 v[140:143], v[130:131], off nt
	global_load_dwordx4 v[136:139], v[128:129], off offset:16 nt
	v_lshl_add_u64 v[128:129], v[210:211], 0, s[52:53]
	global_load_dwordx4 v[132:135], v[130:131], off offset:512 nt
	s_nop 0
	global_load_dwordx4 v[128:131], v[128:129], off offset:16 nt
	s_waitcnt vmcnt(0) lgkmcnt(0)
	s_andn2_b64 vcc, exec, s[28:29]
	s_cbranch_vccnz .Lres_zero_c0
	v_pk_add_f32 v[186:187], v[186:187], 1.0 op_sel_hi:[1,0]
	v_pk_add_f32 v[188:189], v[188:189], 1.0 op_sel_hi:[1,0]
	v_pk_add_f32 v[190:191], v[190:191], 1.0 op_sel_hi:[1,0]
	v_pk_add_f32 v[192:193], v[192:193], 1.0 op_sel_hi:[1,0]
	v_pk_add_f32 v[194:195], v[194:195], 1.0 op_sel_hi:[1,0]
	v_pk_add_f32 v[196:197], v[196:197], 1.0 op_sel_hi:[1,0]
	v_pk_add_f32 v[198:199], v[198:199], 1.0 op_sel_hi:[1,0]
	v_pk_add_f32 v[200:201], v[200:201], 1.0 op_sel_hi:[1,0]
	v_pk_mul_f32 v[238:239], v[238:239], v[186:187]
	v_pk_mul_f32 v[240:241], v[240:241], v[188:189]
	v_pk_mul_f32 v[242:243], v[242:243], v[190:191]
	v_pk_mul_f32 v[244:245], v[244:245], v[192:193]
	v_pk_mul_f32 v[246:247], v[246:247], v[194:195]
	v_pk_mul_f32 v[248:249], v[248:249], v[196:197]
	v_pk_mul_f32 v[250:251], v[250:251], v[198:199]
	v_pk_mul_f32 v[252:253], v[252:253], v[200:201]
	v_mov_b32_e32 v194, v238
	v_mov_b32_e32 v195, v239
	v_mov_b32_e32 v196, v240
	v_mov_b32_e32 v197, v241
	v_mov_b32_e32 v186, v242
	v_mov_b32_e32 v187, v243
	v_mov_b32_e32 v200, v244
	v_mov_b32_e32 v201, v245
	v_mov_b32_e32 v190, v246
	v_mov_b32_e32 v191, v247
	v_mov_b32_e32 v192, v248
	v_mov_b32_e32 v193, v249
	v_mov_b32_e32 v188, v250
	v_mov_b32_e32 v189, v251
	v_mov_b32_e32 v198, v252
	v_mov_b32_e32 v199, v253
	s_branch .Lres_done_c0
.Lres_zero_c0:
	v_mov_b32_e32 v186, 0
	v_mov_b32_e32 v187, 0
	v_mov_b32_e32 v188, 0
	v_mov_b32_e32 v189, 0
	v_mov_b32_e32 v190, 0
	v_mov_b32_e32 v191, 0
	v_mov_b32_e32 v192, 0
	v_mov_b32_e32 v193, 0
	v_mov_b32_e32 v194, 0
	v_mov_b32_e32 v195, 0
	v_mov_b32_e32 v196, 0
	v_mov_b32_e32 v197, 0
	v_mov_b32_e32 v198, 0
	v_mov_b32_e32 v199, 0
	v_mov_b32_e32 v200, 0
	v_mov_b32_e32 v201, 0
.Lres_done_c0:
	s_mov_b32 s55, s51
	s_lshl_b64 s[50:51], s[54:55], 11
	s_add_u32 s52, s60, s50
	s_addc_u32 s53, s61, s51
	s_lshl_b64 s[50:51], s[54:55], 6
	s_waitcnt vmcnt(0) lgkmcnt(0)
	v_pk_mul_f32 v[164:165], v[164:165], 0.5 op_sel_hi:[1,0]
	v_pk_mul_f32 v[160:161], v[160:161], 0.5 op_sel_hi:[1,0]
	v_pk_mul_f32 v[204:205], v[158:159], 0.5 op_sel_hi:[1,0]
	v_pk_mul_f32 v[202:203], v[156:157], 0.5 op_sel_hi:[1,0]
	v_pk_mul_f32 v[206:207], v[146:147], 0.5 op_sel_hi:[1,0]
	v_pk_mul_f32 v[208:209], v[144:145], 0.5 op_sel_hi:[1,0]
	s_add_u32 s50, s70, s50
	v_pk_mul_f32 v[166:167], v[166:167], 0.5 op_sel_hi:[1,0]
	v_pk_mul_f32 v[162:163], v[162:163], 0.5 op_sel_hi:[1,0]
	v_lshl_add_u64 v[212:213], s[40:41], 0, v[178:179]
	s_addc_u32 s51, s71, s51
	s_and_b64 vcc, exec, s[8:9]
	v_pk_fma_f32 v[146:147], v[122:123], v[204:205], v[222:223]
	v_pk_fma_f32 v[158:159], v[126:127], v[206:207], v[234:235]
	v_pk_fma_f32 v[156:157], v[124:125], v[208:209], v[232:233]
	v_pk_fma_f32 v[144:145], v[120:121], v[202:203], v[220:221]
	v_pk_fma_f32 v[124:125], v[116:117], v[160:161], v[152:153]
	v_pk_fma_f32 v[120:121], v[112:113], v[164:165], v[148:149]
	global_store_dwordx4 v[212:213], v[156:159], off nt
	global_store_dwordx4 v[212:213], v[144:147], off offset:16 nt
	s_cbranch_vccnz .LBB0_823
	v_pk_mul_f32 v[116:117], v[194:195], v[156:157]
	v_pk_mul_f32 v[122:123], v[200:201], v[146:147]
	v_cvt_pk_bf16_f32 v220, v116, v117
	v_mul_f32_e32 v116, v157, v157
	v_mul_f32_e32 v117, v159, v159
	v_fmac_f32_e32 v116, v156, v156
	v_fmac_f32_e32 v117, v158, v158
	v_pk_mul_f32 v[112:113], v[196:197], v[158:159]
	v_pk_mul_f32 v[126:127], v[186:187], v[144:145]
	v_cvt_pk_bf16_f32 v221, v112, v113
	v_add_f32_e32 v116, v116, v117
	v_cvt_pk_bf16_f32 v222, v126, v127
	v_cvt_pk_bf16_f32 v223, v122, v123
	v_mul_f32_e32 v117, v145, v145
	v_mul_f32_e32 v122, v147, v147
	v_fmac_f32_e32 v117, v144, v144
	v_fmac_f32_e32 v122, v146, v146
	v_lshl_add_u64 v[112:113], v[176:177], 1, s[52:53]
	v_add_f32_e32 v117, v117, v122
	v_pk_fma_f32 v[126:127], v[118:119], v[162:163], v[154:155]
	v_pk_fma_f32 v[122:123], v[114:115], v[166:167], v[150:151]
	v_pk_mul_f32 v[144:145], v[190:191], v[124:125]
	v_pk_mul_f32 v[146:147], v[188:189], v[120:121]
	global_store_dwordx4 v[112:113], v[220:223], off
	v_add_f32_e32 v152, v116, v117
	global_store_dwordx4 v[212:213], v[124:127], off offset:512 nt
	global_store_dwordx4 v[212:213], v[120:123], off offset:528 nt
	v_pk_mul_f32 v[116:117], v[192:193], v[126:127]
	v_pk_mul_f32 v[148:149], v[198:199], v[122:123]
	v_cvt_pk_bf16_f32 v144, v144, v145
	v_cvt_pk_bf16_f32 v145, v116, v117
	v_cvt_pk_bf16_f32 v146, v146, v147
	v_mul_f32_e32 v116, v123, v123
	v_cvt_pk_bf16_f32 v147, v148, v149
	global_store_dwordx4 v[112:113], v[144:147], off offset:256
	v_mul_f32_e32 v112, v125, v125
	v_mul_f32_e32 v113, v127, v127
	v_fmac_f32_e32 v112, v124, v124
	v_fmac_f32_e32 v113, v126, v126
	v_add_f32_e32 v112, v112, v113
	v_mul_f32_e32 v113, v121, v121
	v_fmac_f32_e32 v113, v120, v120
	v_fmac_f32_e32 v116, v122, v122
	v_add_f32_e32 v113, v113, v116
	v_add_f32_e32 v112, v112, v113
	v_add_f32_e32 v112, v152, v112
	v_mov_b32_e32 v113, v112
	s_nop 1
	v_permlane16_swap_b32_e32 v112, v113
	v_add_f32_e32 v112, v112, v113
	v_mov_b32_e32 v113, v112
	s_nop 1
	v_permlane32_swap_b32_e32 v112, v113
	s_and_saveexec_b64 s[54:55], s[4:5]
	s_cbranch_execz .LBB0_783
	v_add_f32_e32 v116, v112, v113
	v_lshrrev_b32_e32 v112, 4, v176
	s_lshl_b32 s64, s17, 2
	v_and_b32_e32 v112, 0xfffffc0, v112
	v_mov_b32_e32 v113, v177
	s_ashr_i32 s65, s64, 31
	v_lshl_add_u64 v[112:113], s[50:51], 0, v[112:113]
	v_lshl_add_u64 v[112:113], s[64:65], 2, v[112:113]
	s_lshl_b32 s44, s72, 2
	v_lshl_add_u64 v[112:113], v[112:113], 0, s[44:45]
	global_store_dword v[112:113], v116, off

.LBB0_871:
.LBB0_872:
	s_min_i32 s8, s54, 0x80
	s_ashr_i32 s8, s8, 3
	v_lshl_or_b32 v128, s73, 8, v229
	s_mul_i32 s40, s8, 0x9000
	s_mul_hi_i32 s27, s8, 0x9000
	s_add_u32 s8, s76, s40
	v_ashrrev_i32_e32 v129, 31, v128
	s_addc_u32 s9, s77, s27
	v_lshlrev_b64 v[134:135], 2, v[128:129]
	v_lshl_add_u64 v[132:133], s[8:9], 0, v[134:135]
	flat_load_dwordx4 v[144:147], v[132:133]
	s_add_u32 s8, s78, s40
	s_addc_u32 s9, s79, s27
	v_cndmask_b32_e64 v129, 0, 1, s[24:25]
	v_lshl_add_u64 v[130:131], s[48:49], 0, v[134:135]
	v_lshl_add_u64 v[134:135], s[8:9], 0, v[134:135]
	v_cmp_ne_u32_e64 s[8:9], 1, v129
	flat_load_dwordx4 v[156:159], v[132:133] offset:16
	flat_load_dwordx4 v[160:163], v[132:133] offset:512
	flat_load_dwordx4 v[164:167], v[132:133] offset:528
	s_andn2_b64 vcc, exec, s[24:25]
	s_cbranch_vccnz .Lres_pre_skip_c1
	flat_load_dwordx4 v[186:189], v[134:135]
	flat_load_dwordx4 v[238:241], v[130:131]
	flat_load_dwordx4 v[190:193], v[134:135] offset:16
	flat_load_dwordx4 v[242:245], v[130:131] offset:16
	flat_load_dwordx4 v[194:197], v[134:135] offset:512
	flat_load_dwordx4 v[246:249], v[130:131] offset:512
	flat_load_dwordx4 v[198:201], v[134:135] offset:528
	flat_load_dwordx4 v[250:253], v[130:131] offset:528
.Lres_pre_skip_c1:
	s_lshl_b32 s40, s54, 8
	s_add_i32 s44, s40, 0xffff8000
	s_ashr_i32 s41, s40, 31
	s_lshl_b64 s[50:51], s[44:45], 12
	s_add_u32 s27, s14, s50
	s_addc_u32 s52, s15, s51
	s_lshl_b64 s[50:51], s[40:41], 12
	s_add_u32 s53, s10, s50
	s_addc_u32 s55, s11, s51
	s_cmpk_lt_i32 s54, 0x80
	s_cselect_b32 s51, s41, 0
	s_cselect_b32 s50, s40, s44
	s_cselect_b32 s44, s21, s47
	s_cselect_b32 s63, s20, s46
	s_cselect_b32 s54, s40, s40
	s_cselect_b32 s41, s55, s52
	s_cselect_b32 s40, s53, s27
	s_lshl_b64 s[52:53], s[50:51], 12
	s_add_u32 s52, s63, s52
	v_add_u32_e32 v176, v128, v230
	s_addc_u32 s53, s44, s53
	v_lshlrev_b64 v[178:179], 2, v[176:177]
	v_lshl_add_u64 v[210:211], s[52:53], 0, v[178:179]
	s_mov_b32 s27, 0x10000
	s_mov_b64 s[52:53], 0x10000
	v_add_co_u32_e32 v130, vcc, s27, v210
	v_lshl_add_u64 v[128:129], v[210:211], 0, s[52:53]
	s_nop 0
	v_addc_co_u32_e32 v131, vcc, 0, v211, vcc
	s_mov_b64 s[52:53], 0x10200
	global_load_dwordx4 v[220:223], v[210:211], off offset:16 nt
	global_load_dwordx4 v[234:237], v[210:211], off nt
	global_load_dwordx4 v[148:151], v[210:211], off offset:528 nt
	global_load_dwordx4 v[152:155], v[210:211], off offset:512 nt
	global_load_dwordx4 v[140:143], v[130:131], off nt
	global_load_dwordx4 v[136:139], v[128:129], off offset:16 nt
	v_lshl_add_u64 v[128:129], v[210:211], 0, s[52:53]
	global_load_dwordx4 v[132:135], v[130:131], off offset:512 nt
	s_nop 0
	global_load_dwordx4 v[128:131], v[128:129], off offset:16 nt
	s_waitcnt vmcnt(0) lgkmcnt(0)
	s_andn2_b64 vcc, exec, s[24:25]
	s_cbranch_vccnz .Lres_zero_c1
	v_pk_add_f32 v[186:187], v[186:187], 1.0 op_sel_hi:[1,0]
	v_pk_add_f32 v[188:189], v[188:189], 1.0 op_sel_hi:[1,0]
	v_pk_add_f32 v[190:191], v[190:191], 1.0 op_sel_hi:[1,0]
	v_pk_add_f32 v[192:193], v[192:193], 1.0 op_sel_hi:[1,0]
	v_pk_add_f32 v[194:195], v[194:195], 1.0 op_sel_hi:[1,0]
	v_pk_add_f32 v[196:197], v[196:197], 1.0 op_sel_hi:[1,0]
	v_pk_add_f32 v[198:199], v[198:199], 1.0 op_sel_hi:[1,0]
	v_pk_add_f32 v[200:201], v[200:201], 1.0 op_sel_hi:[1,0]
	v_pk_mul_f32 v[238:239], v[238:239], v[186:187]
	v_pk_mul_f32 v[240:241], v[240:241], v[188:189]
	v_pk_mul_f32 v[242:243], v[242:243], v[190:191]
	v_pk_mul_f32 v[244:245], v[244:245], v[192:193]
	v_pk_mul_f32 v[246:247], v[246:247], v[194:195]
	v_pk_mul_f32 v[248:249], v[248:249], v[196:197]
	v_pk_mul_f32 v[250:251], v[250:251], v[198:199]
	v_pk_mul_f32 v[252:253], v[252:253], v[200:201]
	v_mov_b32_e32 v194, v238
	v_mov_b32_e32 v195, v239
	v_mov_b32_e32 v196, v240
	v_mov_b32_e32 v197, v241
	v_mov_b32_e32 v186, v242
	v_mov_b32_e32 v187, v243
	v_mov_b32_e32 v200, v244
	v_mov_b32_e32 v201, v245
	v_mov_b32_e32 v190, v246
	v_mov_b32_e32 v191, v247
	v_mov_b32_e32 v192, v248
	v_mov_b32_e32 v193, v249
	v_mov_b32_e32 v188, v250
	v_mov_b32_e32 v189, v251
	v_mov_b32_e32 v198, v252
	v_mov_b32_e32 v199, v253
	s_branch .Lres_done_c1

.Lres_done_c1:
	s_mov_b32 s55, s51
	s_lshl_b64 s[50:51], s[54:55], 11
	s_add_u32 s52, s60, s50
	s_addc_u32 s53, s61, s51
	s_lshl_b64 s[50:51], s[54:55], 6
	s_waitcnt vmcnt(0) lgkmcnt(0)
	v_pk_mul_f32 v[164:165], v[164:165], 0.5 op_sel_hi:[1,0]
	v_pk_mul_f32 v[160:161], v[160:161], 0.5 op_sel_hi:[1,0]
	v_pk_mul_f32 v[204:205], v[158:159], 0.5 op_sel_hi:[1,0]
	v_pk_mul_f32 v[202:203], v[156:157], 0.5 op_sel_hi:[1,0]
	v_pk_mul_f32 v[208:209], v[146:147], 0.5 op_sel_hi:[1,0]
	v_pk_mul_f32 v[206:207], v[144:145], 0.5 op_sel_hi:[1,0]
	s_add_u32 s50, s70, s50
	v_pk_mul_f32 v[166:167], v[166:167], 0.5 op_sel_hi:[1,0]
	v_pk_mul_f32 v[162:163], v[162:163], 0.5 op_sel_hi:[1,0]
	v_lshl_add_u64 v[212:213], s[40:41], 0, v[178:179]
	s_addc_u32 s51, s71, s51
	s_and_b64 vcc, exec, s[8:9]
	v_pk_fma_f32 v[146:147], v[122:123], v[204:205], v[222:223]
	v_pk_fma_f32 v[158:159], v[126:127], v[208:209], v[236:237]
	v_pk_fma_f32 v[156:157], v[124:125], v[206:207], v[234:235]
	v_pk_fma_f32 v[144:145], v[120:121], v[202:203], v[220:221]
	v_pk_fma_f32 v[124:125], v[116:117], v[160:161], v[152:153]
	v_pk_fma_f32 v[120:121], v[112:113], v[164:165], v[148:149]
	global_store_dwordx4 v[212:213], v[156:159], off nt
	global_store_dwordx4 v[212:213], v[144:147], off offset:16 nt
	s_cbranch_vccnz .LBB0_923
	v_pk_mul_f32 v[116:117], v[194:195], v[156:157]
	v_pk_mul_f32 v[122:123], v[200:201], v[146:147]
	v_cvt_pk_bf16_f32 v220, v116, v117
	v_mul_f32_e32 v116, v157, v157
	v_mul_f32_e32 v117, v159, v159
	v_fmac_f32_e32 v116, v156, v156
	v_fmac_f32_e32 v117, v158, v158
	v_pk_mul_f32 v[112:113], v[196:197], v[158:159]
	v_pk_mul_f32 v[126:127], v[186:187], v[144:145]
	v_cvt_pk_bf16_f32 v221, v112, v113
	v_add_f32_e32 v116, v116, v117
	v_cvt_pk_bf16_f32 v222, v126, v127
	v_cvt_pk_bf16_f32 v223, v122, v123
	v_mul_f32_e32 v117, v145, v145
	v_mul_f32_e32 v122, v147, v147
	v_fmac_f32_e32 v117, v144, v144
	v_fmac_f32_e32 v122, v146, v146
	v_lshl_add_u64 v[112:113], v[176:177], 1, s[52:53]
	v_add_f32_e32 v117, v117, v122
	v_pk_fma_f32 v[126:127], v[118:119], v[162:163], v[154:155]
	v_pk_fma_f32 v[122:123], v[114:115], v[166:167], v[150:151]
	v_pk_mul_f32 v[144:145], v[190:191], v[124:125]
	v_pk_mul_f32 v[146:147], v[188:189], v[120:121]
	global_store_dwordx4 v[112:113], v[220:223], off
	v_add_f32_e32 v152, v116, v117
	global_store_dwordx4 v[212:213], v[124:127], off offset:512 nt
	global_store_dwordx4 v[212:213], v[120:123], off offset:528 nt
	v_pk_mul_f32 v[116:117], v[192:193], v[126:127]
	v_pk_mul_f32 v[148:149], v[198:199], v[122:123]
	v_cvt_pk_bf16_f32 v144, v144, v145
	v_cvt_pk_bf16_f32 v145, v116, v117
	v_cvt_pk_bf16_f32 v146, v146, v147
	v_mul_f32_e32 v116, v123, v123
	v_cvt_pk_bf16_f32 v147, v148, v149
	global_store_dwordx4 v[112:113], v[144:147], off offset:256
	v_mul_f32_e32 v112, v125, v125
	v_mul_f32_e32 v113, v127, v127
	v_fmac_f32_e32 v112, v124, v124
	v_fmac_f32_e32 v113, v126, v126
	v_add_f32_e32 v112, v112, v113
	v_mul_f32_e32 v113, v121, v121
	v_fmac_f32_e32 v113, v120, v120
	v_fmac_f32_e32 v116, v122, v122
	v_add_f32_e32 v113, v113, v116
	v_add_f32_e32 v112, v112, v113
	v_add_f32_e32 v112, v152, v112
	v_mov_b32_e32 v113, v112
	s_nop 1
	v_permlane16_swap_b32_e32 v112, v113
	v_add_f32_e32 v112, v112, v113
	v_mov_b32_e32 v113, v112
	s_nop 1
	v_permlane32_swap_b32_e32 v112, v113
	s_and_saveexec_b64 s[54:55], s[4:5]
	s_cbranch_execz .LBB0_883
	v_add_f32_e32 v116, v112, v113
	v_lshrrev_b32_e32 v112, 4, v176
	s_lshl_b32 s64, s73, 2
	v_and_b32_e32 v112, 0xfffffc0, v112
	v_mov_b32_e32 v113, v177
	s_ashr_i32 s65, s64, 31
	v_lshl_add_u64 v[112:113], s[50:51], 0, v[112:113]
	v_lshl_add_u64 v[112:113], s[64:65], 2, v[112:113]
	s_lshl_b32 s44, s82, 2
	v_lshl_add_u64 v[112:113], v[112:113], 0, s[44:45]
	global_store_dword v[112:113], v116, off

.LBB0_956:
	s_min_i32 s8, s52, 0x80
	s_ashr_i32 s8, s8, 3
	v_lshl_or_b32 v144, s17, 8, v229
	s_mul_i32 s39, s8, 0x9000
	s_mul_hi_i32 s38, s8, 0x9000
	s_add_u32 s8, s76, s39
	v_ashrrev_i32_e32 v145, 31, v144
	s_addc_u32 s9, s77, s38
	v_lshlrev_b64 v[56:57], 2, v[144:145]
	v_lshl_add_u64 v[60:61], s[8:9], 0, v[56:57]
	flat_load_dwordx4 v[64:67], v[60:61]
	s_add_u32 s8, s78, s39
	s_addc_u32 s9, s79, s38
	v_lshl_add_u64 v[146:147], s[48:49], 0, v[56:57]
	v_lshl_add_u64 v[148:149], s[8:9], 0, v[56:57]
	v_cndmask_b32_e64 v56, 0, 1, s[26:27]
	v_cmp_ne_u32_e64 s[8:9], 1, v56
	flat_load_dwordx4 v[68:71], v[60:61] offset:16
	flat_load_dwordx4 v[56:59], v[60:61] offset:512
	flat_load_dwordx4 v[60:63], v[60:61] offset:528
	s_andn2_b64 vcc, exec, s[26:27]
	s_cbranch_vccnz .Lres_pre_skip_c2
	flat_load_dwordx4 v[194:197], v[148:149]
	flat_load_dwordx4 v[238:241], v[146:147]
	flat_load_dwordx4 v[198:201], v[148:149] offset:16
	flat_load_dwordx4 v[242:245], v[146:147] offset:16
	flat_load_dwordx4 v[202:205], v[148:149] offset:512
	flat_load_dwordx4 v[246:249], v[146:147] offset:512
	flat_load_dwordx4 v[206:209], v[148:149] offset:528
	flat_load_dwordx4 v[250:253], v[146:147] offset:528
.Lres_pre_skip_c2:
	s_lshl_b32 s38, s52, 8
	s_add_i32 s44, s38, 0xffff8000
	s_ashr_i32 s39, s38, 31
	s_lshl_b64 s[40:41], s[44:45], 12
	s_add_u32 s50, s14, s40
	s_addc_u32 s51, s15, s41
	s_lshl_b64 s[40:41], s[38:39], 12
	s_add_u32 s53, s10, s40
	s_addc_u32 s64, s11, s41
	s_cmpk_lt_i32 s52, 0x80
	s_cselect_b32 s41, s39, 0
	s_cselect_b32 s40, s38, s44
	s_cselect_b32 s44, s19, s47
	s_cselect_b32 s65, s18, s46
	s_cselect_b32 s52, s38, s38
	s_cselect_b32 s39, s64, s51
	s_cselect_b32 s38, s53, s50
	s_lshl_b64 s[50:51], s[40:41], 12
	s_add_u32 s50, s65, s50
	v_add_u32_e32 v176, v230, v144
	s_addc_u32 s51, s44, s51
	v_lshlrev_b64 v[178:179], 2, v[176:177]
	v_lshl_add_u64 v[210:211], s[50:51], 0, v[178:179]
	s_mov_b32 s40, 0x10000
	s_mov_b64 s[50:51], 0x10000
	v_add_co_u32_e32 v146, vcc, s40, v210
	v_lshl_add_u64 v[144:145], v[210:211], 0, s[50:51]
	s_nop 0
	v_addc_co_u32_e32 v147, vcc, 0, v211, vcc
	s_mov_b64 s[50:51], 0x10200
	global_load_dwordx4 v[168:171], v[210:211], off offset:16 nt
	global_load_dwordx4 v[172:175], v[210:211], off nt
	global_load_dwordx4 v[160:163], v[210:211], off offset:528 nt
	global_load_dwordx4 v[164:167], v[210:211], off offset:512 nt
	global_load_dwordx4 v[156:159], v[146:147], off nt
	global_load_dwordx4 v[152:155], v[144:145], off offset:16 nt
	v_lshl_add_u64 v[144:145], v[210:211], 0, s[50:51]
	global_load_dwordx4 v[148:151], v[146:147], off offset:512 nt
	s_nop 0
	global_load_dwordx4 v[144:147], v[144:145], off offset:16 nt
	s_waitcnt vmcnt(0) lgkmcnt(0)
	s_andn2_b64 vcc, exec, s[26:27]
	s_cbranch_vccnz .Lres_zero_c2
	v_pk_add_f32 v[194:195], v[194:195], 1.0 op_sel_hi:[1,0]
	v_pk_add_f32 v[196:197], v[196:197], 1.0 op_sel_hi:[1,0]
	v_pk_add_f32 v[198:199], v[198:199], 1.0 op_sel_hi:[1,0]
	v_pk_add_f32 v[200:201], v[200:201], 1.0 op_sel_hi:[1,0]
	v_pk_add_f32 v[202:203], v[202:203], 1.0 op_sel_hi:[1,0]
	v_pk_add_f32 v[204:205], v[204:205], 1.0 op_sel_hi:[1,0]
	v_pk_add_f32 v[206:207], v[206:207], 1.0 op_sel_hi:[1,0]
	v_pk_add_f32 v[208:209], v[208:209], 1.0 op_sel_hi:[1,0]
	v_pk_mul_f32 v[238:239], v[238:239], v[194:195]
	v_pk_mul_f32 v[240:241], v[240:241], v[196:197]
	v_pk_mul_f32 v[242:243], v[242:243], v[198:199]
	v_pk_mul_f32 v[244:245], v[244:245], v[200:201]
	v_pk_mul_f32 v[246:247], v[246:247], v[202:203]
	v_pk_mul_f32 v[248:249], v[248:249], v[204:205]
	v_pk_mul_f32 v[250:251], v[250:251], v[206:207]
	v_pk_mul_f32 v[252:253], v[252:253], v[208:209]
	v_mov_b32_e32 v202, v238
	v_mov_b32_e32 v203, v239
	v_mov_b32_e32 v204, v240
	v_mov_b32_e32 v205, v241
	v_mov_b32_e32 v194, v242
	v_mov_b32_e32 v195, v243
	v_mov_b32_e32 v208, v244
	v_mov_b32_e32 v209, v245
	v_mov_b32_e32 v198, v246
	v_mov_b32_e32 v199, v247
	v_mov_b32_e32 v200, v248
	v_mov_b32_e32 v201, v249
	v_mov_b32_e32 v196, v250
	v_mov_b32_e32 v197, v251
	v_mov_b32_e32 v206, v252
	v_mov_b32_e32 v207, v253
	s_branch .Lres_done_c2
.Lres_zero_c2:
	v_mov_b32_e32 v194, 0
	v_mov_b32_e32 v195, 0
	v_mov_b32_e32 v196, 0
	v_mov_b32_e32 v197, 0
	v_mov_b32_e32 v198, 0
	v_mov_b32_e32 v199, 0
	v_mov_b32_e32 v200, 0
	v_mov_b32_e32 v201, 0
	v_mov_b32_e32 v202, 0
	v_mov_b32_e32 v203, 0
	v_mov_b32_e32 v204, 0
	v_mov_b32_e32 v205, 0
	v_mov_b32_e32 v206, 0
	v_mov_b32_e32 v207, 0
	v_mov_b32_e32 v208, 0
	v_mov_b32_e32 v209, 0
.Lres_done_c2:
	s_mov_b32 s53, s41
	s_lshl_b64 s[40:41], s[52:53], 11
	s_add_u32 s50, s58, s40
	s_addc_u32 s51, s59, s41
	s_lshl_b64 s[40:41], s[52:53], 6
	s_add_u32 s40, s70, s40
	v_lshl_add_u64 v[212:213], s[38:39], 0, v[178:179]
	s_addc_u32 s41, s71, s41
	s_and_b64 vcc, exec, s[8:9]
	s_waitcnt vmcnt(0) lgkmcnt(0)
	v_pk_fma_f32 v[170:171], v[138:139], v[70:71], v[170:171]
	v_pk_fma_f32 v[174:175], v[142:143], v[66:67], v[174:175]
	v_pk_fma_f32 v[172:173], v[140:141], v[64:65], v[172:173]
	v_pk_fma_f32 v[168:169], v[136:137], v[68:69], v[168:169]
	v_pk_fma_f32 v[140:141], v[132:133], v[56:57], v[164:165]
	v_pk_fma_f32 v[136:137], v[124:125], v[60:61], v[160:161]
	global_store_dwordx4 v[212:213], v[172:175], off nt
	global_store_dwordx4 v[212:213], v[168:171], off offset:16 nt
	s_cbranch_vccnz .LBB0_1007
	v_pk_mul_f32 v[132:133], v[202:203], v[172:173]
	v_pk_mul_f32 v[138:139], v[208:209], v[170:171]
	v_cvt_pk_bf16_f32 v220, v132, v133
	v_mul_f32_e32 v132, v173, v173
	v_mul_f32_e32 v133, v175, v175
	v_fmac_f32_e32 v132, v172, v172
	v_fmac_f32_e32 v133, v174, v174
	v_pk_mul_f32 v[124:125], v[204:205], v[174:175]
	v_pk_mul_f32 v[142:143], v[194:195], v[168:169]
	v_cvt_pk_bf16_f32 v221, v124, v125
	v_add_f32_e32 v132, v132, v133
	v_cvt_pk_bf16_f32 v222, v142, v143
	v_cvt_pk_bf16_f32 v223, v138, v139
	v_mul_f32_e32 v133, v169, v169
	v_mul_f32_e32 v138, v171, v171
	v_fmac_f32_e32 v133, v168, v168
	v_fmac_f32_e32 v138, v170, v170
	v_lshl_add_u64 v[124:125], v[176:177], 1, s[50:51]
	v_add_f32_e32 v133, v133, v138
	v_pk_fma_f32 v[142:143], v[134:135], v[58:59], v[166:167]
	v_pk_fma_f32 v[138:139], v[126:127], v[62:63], v[162:163]
	v_pk_mul_f32 v[170:171], v[196:197], v[136:137]
	global_store_dwordx4 v[124:125], v[220:223], off
	v_add_f32_e32 v172, v132, v133
	global_store_dwordx4 v[212:213], v[140:143], off offset:512 nt
	global_store_dwordx4 v[212:213], v[136:139], off offset:528 nt
	v_pk_mul_f32 v[132:133], v[200:201], v[142:143]
	v_pk_mul_f32 v[160:161], v[198:199], v[140:141]
	v_pk_mul_f32 v[164:165], v[206:207], v[138:139]
	v_cvt_pk_bf16_f32 v168, v160, v161
	v_cvt_pk_bf16_f32 v169, v132, v133
	v_cvt_pk_bf16_f32 v170, v170, v171
	v_mul_f32_e32 v132, v139, v139
	v_cvt_pk_bf16_f32 v171, v164, v165
	global_store_dwordx4 v[124:125], v[168:171], off offset:256
	v_mul_f32_e32 v124, v141, v141
	v_mul_f32_e32 v125, v143, v143
	v_fmac_f32_e32 v124, v140, v140
	v_fmac_f32_e32 v125, v142, v142
	v_add_f32_e32 v124, v124, v125
	v_mul_f32_e32 v125, v137, v137
	v_fmac_f32_e32 v125, v136, v136
	v_fmac_f32_e32 v132, v138, v138
	v_add_f32_e32 v125, v125, v132
	v_add_f32_e32 v124, v124, v125
	v_add_f32_e32 v124, v172, v124
	v_mov_b32_e32 v125, v124
	s_nop 1
	v_permlane16_swap_b32_e32 v124, v125
	v_add_f32_e32 v124, v124, v125
	v_mov_b32_e32 v125, v124
	s_nop 1
	v_permlane32_swap_b32_e32 v124, v125
	s_and_saveexec_b64 s[52:53], s[4:5]
	s_cbranch_execz .LBB0_967
	v_add_f32_e32 v132, v124, v125
	v_lshrrev_b32_e32 v124, 4, v176
	s_lshl_b32 s64, s17, 2
	v_and_b32_e32 v124, 0xfffffc0, v124
	v_mov_b32_e32 v125, v177
	s_ashr_i32 s65, s64, 31
	v_lshl_add_u64 v[124:125], s[40:41], 0, v[124:125]
	v_lshl_add_u64 v[124:125], s[64:65], 2, v[124:125]
	s_lshl_b32 s44, s68, 2
	v_lshl_add_u64 v[124:125], v[124:125], 0, s[44:45]
	global_store_dword v[124:125], v132, off

.LBB0_1054:
.LBB0_1055:
	s_min_i32 s8, s52, 0x80
	s_ashr_i32 s8, s8, 3
	v_lshl_or_b32 v144, s69, 8, v229
	s_mul_i32 s38, s8, 0x9000
	s_mul_hi_i32 s25, s8, 0x9000
	s_add_u32 s8, s76, s38
	v_ashrrev_i32_e32 v145, 31, v144
	s_addc_u32 s9, s77, s25
	v_lshlrev_b64 v[88:89], 2, v[144:145]
	v_lshl_add_u64 v[92:93], s[8:9], 0, v[88:89]
	flat_load_dwordx4 v[104:107], v[92:93]
	s_add_u32 s8, s78, s38
	s_addc_u32 s9, s79, s25
	v_lshl_add_u64 v[146:147], s[48:49], 0, v[88:89]
	v_lshl_add_u64 v[148:149], s[8:9], 0, v[88:89]
	v_cndmask_b32_e64 v88, 0, 1, s[22:23]
	v_cmp_ne_u32_e64 s[8:9], 1, v88
	flat_load_dwordx4 v[108:111], v[92:93] offset:16
	flat_load_dwordx4 v[88:91], v[92:93] offset:512
	flat_load_dwordx4 v[92:95], v[92:93] offset:528
	s_andn2_b64 vcc, exec, s[22:23]
	s_cbranch_vccnz .Lres_pre_skip_c3
	flat_load_dwordx4 v[194:197], v[148:149]
	flat_load_dwordx4 v[238:241], v[146:147]
	flat_load_dwordx4 v[198:201], v[148:149] offset:16
	flat_load_dwordx4 v[242:245], v[146:147] offset:16
	flat_load_dwordx4 v[202:205], v[148:149] offset:512
	flat_load_dwordx4 v[246:249], v[146:147] offset:512
	flat_load_dwordx4 v[206:209], v[148:149] offset:528
	flat_load_dwordx4 v[250:253], v[146:147] offset:528
.Lres_pre_skip_c3:
	s_lshl_b32 s38, s52, 8
	s_add_i32 s44, s38, 0xffff8000
	s_ashr_i32 s39, s38, 31
	s_lshl_b64 s[40:41], s[44:45], 12
	s_add_u32 s25, s14, s40
	s_addc_u32 s50, s15, s41
	s_lshl_b64 s[40:41], s[38:39], 12
	s_add_u32 s51, s10, s40
	s_addc_u32 s53, s11, s41
	s_cmpk_lt_i32 s52, 0x80
	s_cselect_b32 s41, s39, 0
	s_cselect_b32 s40, s38, s44
	s_cselect_b32 s44, s19, s47
	s_cselect_b32 s63, s18, s46
	s_cselect_b32 s52, s38, s38
	s_cselect_b32 s39, s53, s50
	s_cselect_b32 s38, s51, s25
	s_lshl_b64 s[50:51], s[40:41], 12
	s_add_u32 s50, s63, s50
	v_add_u32_e32 v176, v144, v230
	s_addc_u32 s51, s44, s51
	v_lshlrev_b64 v[178:179], 2, v[176:177]
	v_lshl_add_u64 v[210:211], s[50:51], 0, v[178:179]
	s_mov_b32 s25, 0x10000
	s_mov_b64 s[50:51], 0x10000
	v_add_co_u32_e32 v146, vcc, s25, v210
	v_lshl_add_u64 v[144:145], v[210:211], 0, s[50:51]
	s_nop 0
	v_addc_co_u32_e32 v147, vcc, 0, v211, vcc
	s_mov_b64 s[50:51], 0x10200
	global_load_dwordx4 v[168:171], v[210:211], off offset:16 nt
	global_load_dwordx4 v[172:175], v[210:211], off nt
	global_load_dwordx4 v[160:163], v[210:211], off offset:528 nt
	global_load_dwordx4 v[164:167], v[210:211], off offset:512 nt
	global_load_dwordx4 v[156:159], v[146:147], off nt
	global_load_dwordx4 v[152:155], v[144:145], off offset:16 nt
	v_lshl_add_u64 v[144:145], v[210:211], 0, s[50:51]
	global_load_dwordx4 v[148:151], v[146:147], off offset:512 nt
	s_nop 0
	global_load_dwordx4 v[144:147], v[144:145], off offset:16 nt
	s_waitcnt vmcnt(0) lgkmcnt(0)
	s_andn2_b64 vcc, exec, s[22:23]
	s_cbranch_vccnz .Lres_zero_c3
	v_pk_add_f32 v[194:195], v[194:195], 1.0 op_sel_hi:[1,0]
	v_pk_add_f32 v[196:197], v[196:197], 1.0 op_sel_hi:[1,0]
	v_pk_add_f32 v[198:199], v[198:199], 1.0 op_sel_hi:[1,0]
	v_pk_add_f32 v[200:201], v[200:201], 1.0 op_sel_hi:[1,0]
	v_pk_add_f32 v[202:203], v[202:203], 1.0 op_sel_hi:[1,0]
	v_pk_add_f32 v[204:205], v[204:205], 1.0 op_sel_hi:[1,0]
	v_pk_add_f32 v[206:207], v[206:207], 1.0 op_sel_hi:[1,0]
	v_pk_add_f32 v[208:209], v[208:209], 1.0 op_sel_hi:[1,0]
	v_pk_mul_f32 v[238:239], v[238:239], v[194:195]
	v_pk_mul_f32 v[240:241], v[240:241], v[196:197]
	v_pk_mul_f32 v[242:243], v[242:243], v[198:199]
	v_pk_mul_f32 v[244:245], v[244:245], v[200:201]
	v_pk_mul_f32 v[246:247], v[246:247], v[202:203]
	v_pk_mul_f32 v[248:249], v[248:249], v[204:205]
	v_pk_mul_f32 v[250:251], v[250:251], v[206:207]
	v_pk_mul_f32 v[252:253], v[252:253], v[208:209]
	v_mov_b32_e32 v202, v238
	v_mov_b32_e32 v203, v239
	v_mov_b32_e32 v204, v240
	v_mov_b32_e32 v205, v241
	v_mov_b32_e32 v194, v242
	v_mov_b32_e32 v195, v243
	v_mov_b32_e32 v208, v244
	v_mov_b32_e32 v209, v245
	v_mov_b32_e32 v198, v246
	v_mov_b32_e32 v199, v247
	v_mov_b32_e32 v200, v248
	v_mov_b32_e32 v201, v249
	v_mov_b32_e32 v196, v250
	v_mov_b32_e32 v197, v251
	v_mov_b32_e32 v206, v252
	v_mov_b32_e32 v207, v253
	s_branch .Lres_done_c3

.Lres_done_c3:
	s_mov_b32 s53, s41
	s_lshl_b64 s[40:41], s[52:53], 11
	s_add_u32 s50, s58, s40
	s_addc_u32 s51, s59, s41
	s_lshl_b64 s[40:41], s[52:53], 6
	s_add_u32 s40, s70, s40
	v_lshl_add_u64 v[212:213], s[38:39], 0, v[178:179]
	s_addc_u32 s41, s71, s41
	s_and_b64 vcc, exec, s[8:9]
	s_waitcnt vmcnt(0) lgkmcnt(0)
	v_pk_fma_f32 v[170:171], v[138:139], v[110:111], v[170:171]
	v_pk_fma_f32 v[174:175], v[142:143], v[106:107], v[174:175]
	v_pk_fma_f32 v[172:173], v[140:141], v[104:105], v[172:173]
	v_pk_fma_f32 v[168:169], v[136:137], v[108:109], v[168:169]
	v_pk_fma_f32 v[140:141], v[132:133], v[88:89], v[164:165]
	v_pk_fma_f32 v[136:137], v[128:129], v[92:93], v[160:161]
	global_store_dwordx4 v[212:213], v[172:175], off nt
	global_store_dwordx4 v[212:213], v[168:171], off offset:16 nt
	s_cbranch_vccnz .LBB0_1106
	v_pk_mul_f32 v[132:133], v[202:203], v[172:173]
	v_pk_mul_f32 v[138:139], v[208:209], v[170:171]
	v_cvt_pk_bf16_f32 v220, v132, v133
	v_mul_f32_e32 v132, v173, v173
	v_mul_f32_e32 v133, v175, v175
	v_fmac_f32_e32 v132, v172, v172
	v_fmac_f32_e32 v133, v174, v174
	v_pk_mul_f32 v[128:129], v[204:205], v[174:175]
	v_pk_mul_f32 v[142:143], v[194:195], v[168:169]
	v_cvt_pk_bf16_f32 v221, v128, v129
	v_add_f32_e32 v132, v132, v133
	v_cvt_pk_bf16_f32 v222, v142, v143
	v_cvt_pk_bf16_f32 v223, v138, v139
	v_mul_f32_e32 v133, v169, v169
	v_mul_f32_e32 v138, v171, v171
	v_fmac_f32_e32 v133, v168, v168
	v_fmac_f32_e32 v138, v170, v170
	v_lshl_add_u64 v[128:129], v[176:177], 1, s[50:51]
	v_add_f32_e32 v133, v133, v138
	v_pk_fma_f32 v[142:143], v[134:135], v[90:91], v[166:167]
	v_pk_fma_f32 v[138:139], v[130:131], v[94:95], v[162:163]
	v_pk_mul_f32 v[170:171], v[196:197], v[136:137]
	global_store_dwordx4 v[128:129], v[220:223], off
	v_add_f32_e32 v172, v132, v133
	global_store_dwordx4 v[212:213], v[140:143], off offset:512 nt
	global_store_dwordx4 v[212:213], v[136:139], off offset:528 nt
	v_pk_mul_f32 v[132:133], v[200:201], v[142:143]
	v_pk_mul_f32 v[160:161], v[198:199], v[140:141]
	v_pk_mul_f32 v[164:165], v[206:207], v[138:139]
	v_cvt_pk_bf16_f32 v168, v160, v161
	v_cvt_pk_bf16_f32 v169, v132, v133
	v_cvt_pk_bf16_f32 v170, v170, v171
	v_mul_f32_e32 v132, v139, v139
	v_cvt_pk_bf16_f32 v171, v164, v165
	global_store_dwordx4 v[128:129], v[168:171], off offset:256
	v_mul_f32_e32 v128, v141, v141
	v_mul_f32_e32 v129, v143, v143
	v_fmac_f32_e32 v128, v140, v140
	v_fmac_f32_e32 v129, v142, v142
	v_add_f32_e32 v128, v128, v129
	v_mul_f32_e32 v129, v137, v137
	v_fmac_f32_e32 v129, v136, v136
	v_fmac_f32_e32 v132, v138, v138
	v_add_f32_e32 v129, v129, v132
	v_add_f32_e32 v128, v128, v129
	v_add_f32_e32 v128, v172, v128
	v_mov_b32_e32 v129, v128
	s_nop 1
	v_permlane16_swap_b32_e32 v128, v129
	v_add_f32_e32 v128, v128, v129
	v_mov_b32_e32 v129, v128
	s_nop 1
	v_permlane32_swap_b32_e32 v128, v129
	s_and_saveexec_b64 s[52:53], s[4:5]
	s_cbranch_execz .LBB0_1066
	v_add_f32_e32 v132, v128, v129
	v_lshrrev_b32_e32 v128, 4, v176
	s_lshl_b32 s64, s69, 2
	v_and_b32_e32 v128, 0xfffffc0, v128
	v_mov_b32_e32 v129, v177
	s_ashr_i32 s65, s64, 31
	v_lshl_add_u64 v[128:129], s[40:41], 0, v[128:129]
	v_lshl_add_u64 v[128:129], s[64:65], 2, v[128:129]
	s_lshl_b32 s44, s80, 2
	v_lshl_add_u64 v[128:129], v[128:129], 0, s[44:45]
	global_store_dword v[128:129], v132, off

.LBB0_1134:
	s_min_i32 s6, s40, 0x80
	s_ashr_i32 s6, s6, 3
	v_lshl_or_b32 v144, s16, 8, v229
	s_mul_i32 s27, s6, 0x9000
	s_mul_hi_i32 s25, s6, 0x9000
	s_add_u32 s6, s76, s27
	v_ashrrev_i32_e32 v145, 31, v144
	s_addc_u32 s7, s77, s25
	v_lshlrev_b64 v[56:57], 2, v[144:145]
	v_lshl_add_u64 v[60:61], s[6:7], 0, v[56:57]
	flat_load_dwordx4 v[64:67], v[60:61]
	s_add_u32 s6, s78, s27
	s_addc_u32 s7, s79, s25
	v_lshl_add_u64 v[146:147], s[48:49], 0, v[56:57]
	v_lshl_add_u64 v[148:149], s[6:7], 0, v[56:57]
	v_cndmask_b32_e64 v56, 0, 1, s[22:23]
	v_cmp_ne_u32_e64 s[6:7], 1, v56
	flat_load_dwordx4 v[68:71], v[60:61] offset:16
	flat_load_dwordx4 v[56:59], v[60:61] offset:512
	flat_load_dwordx4 v[60:63], v[60:61] offset:528
	s_andn2_b64 vcc, exec, s[22:23]
	s_cbranch_vccnz .Lres_pre_skip_c4
	flat_load_dwordx4 v[194:197], v[148:149]
	flat_load_dwordx4 v[238:241], v[146:147]
	flat_load_dwordx4 v[198:201], v[148:149] offset:16
	flat_load_dwordx4 v[242:245], v[146:147] offset:16
	flat_load_dwordx4 v[202:205], v[148:149] offset:512
	flat_load_dwordx4 v[246:249], v[146:147] offset:512
	flat_load_dwordx4 v[206:209], v[148:149] offset:528
	flat_load_dwordx4 v[250:253], v[146:147] offset:528
.Lres_pre_skip_c4:
	s_lshl_b32 s42, s40, 8
	s_add_i32 s44, s42, 0xffff8000
	s_ashr_i32 s43, s42, 31
	s_lshl_b64 s[50:51], s[44:45], 12
	s_add_u32 s25, s14, s50
	s_addc_u32 s27, s15, s51
	s_lshl_b64 s[50:51], s[42:43], 12
	s_add_u32 s52, s10, s50
	s_addc_u32 s41, s11, s51
	s_cmpk_lt_i32 s40, 0x80
	s_cselect_b32 s51, s43, 0
	s_cselect_b32 s50, s42, s44
	s_cselect_b32 s43, s1, s47
	s_cselect_b32 s44, s0, s46
	s_cselect_b32 s42, s42, s42
	s_cselect_b32 s41, s41, s27
	s_cselect_b32 s40, s52, s25
	s_lshl_b64 s[52:53], s[50:51], 12
	s_add_u32 s52, s44, s52
	v_add_u32_e32 v176, v230, v144
	s_addc_u32 s53, s43, s53
	v_lshlrev_b64 v[178:179], 2, v[176:177]
	v_lshl_add_u64 v[210:211], s[52:53], 0, v[178:179]
	s_mov_b32 s25, 0x10000
	s_mov_b64 s[52:53], 0x10000
	v_add_co_u32_e32 v146, vcc, s25, v210
	v_lshl_add_u64 v[144:145], v[210:211], 0, s[52:53]
	s_nop 0
	v_addc_co_u32_e32 v147, vcc, 0, v211, vcc
	s_mov_b64 s[52:53], 0x10200
	global_load_dwordx4 v[168:171], v[210:211], off offset:16 nt
	global_load_dwordx4 v[172:175], v[210:211], off nt
	global_load_dwordx4 v[160:163], v[210:211], off offset:528 nt
	global_load_dwordx4 v[164:167], v[210:211], off offset:512 nt
	global_load_dwordx4 v[156:159], v[146:147], off nt
	global_load_dwordx4 v[152:155], v[144:145], off offset:16 nt
	v_lshl_add_u64 v[144:145], v[210:211], 0, s[52:53]
	global_load_dwordx4 v[148:151], v[146:147], off offset:512 nt
	s_nop 0
	global_load_dwordx4 v[144:147], v[144:145], off offset:16 nt
	s_waitcnt vmcnt(0) lgkmcnt(0)
	s_andn2_b64 vcc, exec, s[22:23]
	s_cbranch_vccnz .Lres_zero_c4
	v_pk_add_f32 v[194:195], v[194:195], 1.0 op_sel_hi:[1,0]
	v_pk_add_f32 v[196:197], v[196:197], 1.0 op_sel_hi:[1,0]
	v_pk_add_f32 v[198:199], v[198:199], 1.0 op_sel_hi:[1,0]
	v_pk_add_f32 v[200:201], v[200:201], 1.0 op_sel_hi:[1,0]
	v_pk_add_f32 v[202:203], v[202:203], 1.0 op_sel_hi:[1,0]
	v_pk_add_f32 v[204:205], v[204:205], 1.0 op_sel_hi:[1,0]
	v_pk_add_f32 v[206:207], v[206:207], 1.0 op_sel_hi:[1,0]
	v_pk_add_f32 v[208:209], v[208:209], 1.0 op_sel_hi:[1,0]
	v_pk_mul_f32 v[238:239], v[238:239], v[194:195]
	v_pk_mul_f32 v[240:241], v[240:241], v[196:197]
	v_pk_mul_f32 v[242:243], v[242:243], v[198:199]
	v_pk_mul_f32 v[244:245], v[244:245], v[200:201]
	v_pk_mul_f32 v[246:247], v[246:247], v[202:203]
	v_pk_mul_f32 v[248:249], v[248:249], v[204:205]
	v_pk_mul_f32 v[250:251], v[250:251], v[206:207]
	v_pk_mul_f32 v[252:253], v[252:253], v[208:209]
	v_mov_b32_e32 v202, v238
	v_mov_b32_e32 v203, v239
	v_mov_b32_e32 v204, v240
	v_mov_b32_e32 v205, v241
	v_mov_b32_e32 v194, v242
	v_mov_b32_e32 v195, v243
	v_mov_b32_e32 v208, v244
	v_mov_b32_e32 v209, v245
	v_mov_b32_e32 v198, v246
	v_mov_b32_e32 v199, v247
	v_mov_b32_e32 v200, v248
	v_mov_b32_e32 v201, v249
	v_mov_b32_e32 v196, v250
	v_mov_b32_e32 v197, v251
	v_mov_b32_e32 v206, v252
	v_mov_b32_e32 v207, v253
	s_branch .Lres_done_c4

.Lres_done_c4:
	s_mov_b32 s43, s51
	s_lshl_b64 s[50:51], s[42:43], 11
	s_add_u32 s50, s60, s50
	s_addc_u32 s51, s61, s51
	s_lshl_b64 s[42:43], s[42:43], 6
	s_add_u32 s42, s70, s42
	v_lshl_add_u64 v[212:213], s[40:41], 0, v[178:179]
	s_addc_u32 s43, s71, s43
	s_and_b64 vcc, exec, s[6:7]
	s_waitcnt vmcnt(0) lgkmcnt(0)
	v_pk_fma_f32 v[170:171], v[138:139], v[70:71], v[170:171]
	v_pk_fma_f32 v[174:175], v[142:143], v[66:67], v[174:175]
	v_pk_fma_f32 v[172:173], v[140:141], v[64:65], v[172:173]
	v_pk_fma_f32 v[168:169], v[136:137], v[68:69], v[168:169]
	v_pk_fma_f32 v[140:141], v[132:133], v[56:57], v[164:165]
	v_pk_fma_f32 v[136:137], v[124:125], v[60:61], v[160:161]
	global_store_dwordx4 v[212:213], v[172:175], off nt
	global_store_dwordx4 v[212:213], v[168:171], off offset:16 nt
	s_cbranch_vccnz .LBB0_1185
	v_pk_mul_f32 v[132:133], v[202:203], v[172:173]
	v_pk_mul_f32 v[138:139], v[208:209], v[170:171]
	v_cvt_pk_bf16_f32 v220, v132, v133
	v_mul_f32_e32 v132, v173, v173
	v_mul_f32_e32 v133, v175, v175
	v_fmac_f32_e32 v132, v172, v172
	v_fmac_f32_e32 v133, v174, v174
	v_pk_mul_f32 v[124:125], v[204:205], v[174:175]
	v_pk_mul_f32 v[142:143], v[194:195], v[168:169]
	v_cvt_pk_bf16_f32 v221, v124, v125
	v_add_f32_e32 v132, v132, v133
	v_cvt_pk_bf16_f32 v222, v142, v143
	v_cvt_pk_bf16_f32 v223, v138, v139
	v_mul_f32_e32 v133, v169, v169
	v_mul_f32_e32 v138, v171, v171
	v_fmac_f32_e32 v133, v168, v168
	v_fmac_f32_e32 v138, v170, v170
	v_lshl_add_u64 v[124:125], v[176:177], 1, s[50:51]
	v_add_f32_e32 v133, v133, v138
	v_pk_fma_f32 v[142:143], v[134:135], v[58:59], v[166:167]
	v_pk_fma_f32 v[138:139], v[126:127], v[62:63], v[162:163]
	v_pk_mul_f32 v[170:171], v[196:197], v[136:137]
	global_store_dwordx4 v[124:125], v[220:223], off
	v_add_f32_e32 v172, v132, v133
	global_store_dwordx4 v[212:213], v[140:143], off offset:512 nt
	global_store_dwordx4 v[212:213], v[136:139], off offset:528 nt
	v_pk_mul_f32 v[132:133], v[200:201], v[142:143]
	v_pk_mul_f32 v[160:161], v[198:199], v[140:141]
	v_pk_mul_f32 v[164:165], v[206:207], v[138:139]
	v_cvt_pk_bf16_f32 v168, v160, v161
	v_cvt_pk_bf16_f32 v169, v132, v133
	v_cvt_pk_bf16_f32 v170, v170, v171
	v_mul_f32_e32 v132, v139, v139
	v_cvt_pk_bf16_f32 v171, v164, v165
	global_store_dwordx4 v[124:125], v[168:171], off offset:256
	v_mul_f32_e32 v124, v141, v141
	v_mul_f32_e32 v125, v143, v143
	v_fmac_f32_e32 v124, v140, v140
	v_fmac_f32_e32 v125, v142, v142
	v_add_f32_e32 v124, v124, v125
	v_mul_f32_e32 v125, v137, v137
	v_fmac_f32_e32 v125, v136, v136
	v_fmac_f32_e32 v132, v138, v138
	v_add_f32_e32 v125, v125, v132
	v_add_f32_e32 v124, v124, v125
	v_add_f32_e32 v124, v172, v124
	v_mov_b32_e32 v125, v124
	s_nop 1
	v_permlane16_swap_b32_e32 v124, v125
	v_add_f32_e32 v124, v124, v125
	v_mov_b32_e32 v125, v124
	s_nop 1
	v_permlane32_swap_b32_e32 v124, v125
	s_and_saveexec_b64 s[52:53], s[2:3]
	s_cbranch_execz .LBB0_1145
	v_add_f32_e32 v132, v124, v125
	v_lshrrev_b32_e32 v124, 4, v176
	s_lshl_b32 s64, s16, 2
	v_and_b32_e32 v124, 0xfffffc0, v124
	v_mov_b32_e32 v125, v177
	s_ashr_i32 s65, s64, 31
	v_lshl_add_u64 v[124:125], s[42:43], 0, v[124:125]
	v_lshl_add_u64 v[124:125], s[64:65], 2, v[124:125]
	s_lshl_b32 s44, s74, 2
	v_lshl_add_u64 v[124:125], v[124:125], 0, s[44:45]
	global_store_dword v[124:125], v132, off

.LBB0_1228:
.LBB0_1229:
	s_min_i32 s4, s40, 0x80
	s_ashr_i32 s4, s4, 3
	v_lshl_or_b32 v144, s6, 8, v229
	s_mul_i32 s23, s4, 0x9000
	s_mul_hi_i32 s21, s4, 0x9000
	s_add_u32 s4, s76, s23
	v_ashrrev_i32_e32 v145, 31, v144
	s_addc_u32 s5, s77, s21
	v_lshlrev_b64 v[88:89], 2, v[144:145]
	v_lshl_add_u64 v[92:93], s[4:5], 0, v[88:89]
	flat_load_dwordx4 v[104:107], v[92:93]
	s_add_u32 s4, s78, s23
	s_addc_u32 s5, s79, s21
	v_lshl_add_u64 v[146:147], s[48:49], 0, v[88:89]
	v_lshl_add_u64 v[148:149], s[4:5], 0, v[88:89]
	v_cndmask_b32_e64 v88, 0, 1, s[18:19]
	v_cmp_ne_u32_e64 s[4:5], 1, v88
	flat_load_dwordx4 v[108:111], v[92:93] offset:16
	flat_load_dwordx4 v[88:91], v[92:93] offset:512
	flat_load_dwordx4 v[92:95], v[92:93] offset:528
	s_andn2_b64 vcc, exec, s[18:19]
	s_cbranch_vccnz .Lres_pre_skip_c5
	flat_load_dwordx4 v[194:197], v[148:149]
	flat_load_dwordx4 v[238:241], v[146:147]
	flat_load_dwordx4 v[198:201], v[148:149] offset:16
	flat_load_dwordx4 v[242:245], v[146:147] offset:16
	flat_load_dwordx4 v[202:205], v[148:149] offset:512
	flat_load_dwordx4 v[246:249], v[146:147] offset:512
	flat_load_dwordx4 v[206:209], v[148:149] offset:528
	flat_load_dwordx4 v[250:253], v[146:147] offset:528
.Lres_pre_skip_c5:
	s_lshl_b32 s42, s40, 8
	s_add_i32 s44, s42, 0xffff8000
	s_ashr_i32 s43, s42, 31
	s_lshl_b64 s[50:51], s[44:45], 12
	s_add_u32 s21, s14, s50
	s_addc_u32 s23, s15, s51
	s_lshl_b64 s[50:51], s[42:43], 12
	s_add_u32 s27, s10, s50
	s_addc_u32 s41, s11, s51
	s_cmpk_lt_i32 s40, 0x80
	s_cselect_b32 s51, s43, 0
	s_cselect_b32 s50, s42, s44
	s_cselect_b32 s43, s1, s47
	s_cselect_b32 s44, s0, s46
	s_cselect_b32 s42, s42, s42
	s_cselect_b32 s41, s41, s23
	s_cselect_b32 s40, s27, s21
	s_lshl_b64 s[52:53], s[50:51], 12
	s_add_u32 s52, s44, s52
	v_add_u32_e32 v176, v144, v230
	s_addc_u32 s53, s43, s53
	v_lshlrev_b64 v[178:179], 2, v[176:177]
	v_lshl_add_u64 v[210:211], s[52:53], 0, v[178:179]
	s_mov_b32 s21, 0x10000
	s_mov_b64 s[52:53], 0x10000
	v_add_co_u32_e32 v146, vcc, s21, v210
	v_lshl_add_u64 v[144:145], v[210:211], 0, s[52:53]
	s_nop 0
	v_addc_co_u32_e32 v147, vcc, 0, v211, vcc
	s_mov_b64 s[52:53], 0x10200
	global_load_dwordx4 v[168:171], v[210:211], off offset:16 nt
	global_load_dwordx4 v[172:175], v[210:211], off nt
	global_load_dwordx4 v[160:163], v[210:211], off offset:528 nt
	global_load_dwordx4 v[164:167], v[210:211], off offset:512 nt
	global_load_dwordx4 v[156:159], v[146:147], off nt
	global_load_dwordx4 v[152:155], v[144:145], off offset:16 nt
	v_lshl_add_u64 v[144:145], v[210:211], 0, s[52:53]
	global_load_dwordx4 v[148:151], v[146:147], off offset:512 nt
	s_nop 0
	global_load_dwordx4 v[144:147], v[144:145], off offset:16 nt
	s_waitcnt vmcnt(0) lgkmcnt(0)
	s_andn2_b64 vcc, exec, s[18:19]
	s_cbranch_vccnz .Lres_zero_c5
	v_pk_add_f32 v[194:195], v[194:195], 1.0 op_sel_hi:[1,0]
	v_pk_add_f32 v[196:197], v[196:197], 1.0 op_sel_hi:[1,0]
	v_pk_add_f32 v[198:199], v[198:199], 1.0 op_sel_hi:[1,0]
	v_pk_add_f32 v[200:201], v[200:201], 1.0 op_sel_hi:[1,0]
	v_pk_add_f32 v[202:203], v[202:203], 1.0 op_sel_hi:[1,0]
	v_pk_add_f32 v[204:205], v[204:205], 1.0 op_sel_hi:[1,0]
	v_pk_add_f32 v[206:207], v[206:207], 1.0 op_sel_hi:[1,0]
	v_pk_add_f32 v[208:209], v[208:209], 1.0 op_sel_hi:[1,0]
	v_pk_mul_f32 v[238:239], v[238:239], v[194:195]
	v_pk_mul_f32 v[240:241], v[240:241], v[196:197]
	v_pk_mul_f32 v[242:243], v[242:243], v[198:199]
	v_pk_mul_f32 v[244:245], v[244:245], v[200:201]
	v_pk_mul_f32 v[246:247], v[246:247], v[202:203]
	v_pk_mul_f32 v[248:249], v[248:249], v[204:205]
	v_pk_mul_f32 v[250:251], v[250:251], v[206:207]
	v_pk_mul_f32 v[252:253], v[252:253], v[208:209]
	v_mov_b32_e32 v202, v238
	v_mov_b32_e32 v203, v239
	v_mov_b32_e32 v204, v240
	v_mov_b32_e32 v205, v241
	v_mov_b32_e32 v194, v242
	v_mov_b32_e32 v195, v243
	v_mov_b32_e32 v208, v244
	v_mov_b32_e32 v209, v245
	v_mov_b32_e32 v198, v246
	v_mov_b32_e32 v199, v247
	v_mov_b32_e32 v200, v248
	v_mov_b32_e32 v201, v249
	v_mov_b32_e32 v196, v250
	v_mov_b32_e32 v197, v251
	v_mov_b32_e32 v206, v252
	v_mov_b32_e32 v207, v253
	s_branch .Lres_done_c5

.Lres_done_c5:
	s_mov_b32 s43, s51
	s_lshl_b64 s[50:51], s[42:43], 11
	s_add_u32 s50, s60, s50
	s_addc_u32 s51, s61, s51
	s_lshl_b64 s[42:43], s[42:43], 6
	s_add_u32 s42, s70, s42
	v_lshl_add_u64 v[212:213], s[40:41], 0, v[178:179]
	s_addc_u32 s43, s71, s43
	s_and_b64 vcc, exec, s[4:5]
	s_waitcnt vmcnt(0) lgkmcnt(0)
	v_pk_fma_f32 v[170:171], v[138:139], v[110:111], v[170:171]
	v_pk_fma_f32 v[174:175], v[142:143], v[106:107], v[174:175]
	v_pk_fma_f32 v[172:173], v[140:141], v[104:105], v[172:173]
	v_pk_fma_f32 v[168:169], v[136:137], v[108:109], v[168:169]
	v_pk_fma_f32 v[140:141], v[132:133], v[88:89], v[164:165]
	v_pk_fma_f32 v[136:137], v[128:129], v[92:93], v[160:161]
	global_store_dwordx4 v[212:213], v[172:175], off nt
	global_store_dwordx4 v[212:213], v[168:171], off offset:16 nt
	s_cbranch_vccnz .LBB0_1280
	v_pk_mul_f32 v[132:133], v[202:203], v[172:173]
	v_pk_mul_f32 v[138:139], v[208:209], v[170:171]
	v_cvt_pk_bf16_f32 v220, v132, v133
	v_mul_f32_e32 v132, v173, v173
	v_mul_f32_e32 v133, v175, v175
	v_fmac_f32_e32 v132, v172, v172
	v_fmac_f32_e32 v133, v174, v174
	v_pk_mul_f32 v[128:129], v[204:205], v[174:175]
	v_pk_mul_f32 v[142:143], v[194:195], v[168:169]
	v_cvt_pk_bf16_f32 v221, v128, v129
	v_add_f32_e32 v132, v132, v133
	v_cvt_pk_bf16_f32 v222, v142, v143
	v_cvt_pk_bf16_f32 v223, v138, v139
	v_mul_f32_e32 v133, v169, v169
	v_mul_f32_e32 v138, v171, v171
	v_fmac_f32_e32 v133, v168, v168
	v_fmac_f32_e32 v138, v170, v170
	v_lshl_add_u64 v[128:129], v[176:177], 1, s[50:51]
	v_add_f32_e32 v133, v133, v138
	v_pk_fma_f32 v[142:143], v[134:135], v[90:91], v[166:167]
	v_pk_fma_f32 v[138:139], v[130:131], v[94:95], v[162:163]
	v_pk_mul_f32 v[170:171], v[196:197], v[136:137]
	global_store_dwordx4 v[128:129], v[220:223], off
	v_add_f32_e32 v172, v132, v133
	global_store_dwordx4 v[212:213], v[140:143], off offset:512 nt
	global_store_dwordx4 v[212:213], v[136:139], off offset:528 nt
	v_pk_mul_f32 v[132:133], v[200:201], v[142:143]
	v_pk_mul_f32 v[160:161], v[198:199], v[140:141]
	v_pk_mul_f32 v[164:165], v[206:207], v[138:139]
	v_cvt_pk_bf16_f32 v168, v160, v161
	v_cvt_pk_bf16_f32 v169, v132, v133
	v_cvt_pk_bf16_f32 v170, v170, v171
	v_mul_f32_e32 v132, v139, v139
	v_cvt_pk_bf16_f32 v171, v164, v165
	global_store_dwordx4 v[128:129], v[168:171], off offset:256
	v_mul_f32_e32 v128, v141, v141
	v_mul_f32_e32 v129, v143, v143
	v_fmac_f32_e32 v128, v140, v140
	v_fmac_f32_e32 v129, v142, v142
	v_add_f32_e32 v128, v128, v129
	v_mul_f32_e32 v129, v137, v137
	v_fmac_f32_e32 v129, v136, v136
	v_fmac_f32_e32 v132, v138, v138
	v_add_f32_e32 v129, v129, v132
	v_add_f32_e32 v128, v128, v129
	v_add_f32_e32 v128, v172, v128
	v_mov_b32_e32 v129, v128
	s_nop 1
	v_permlane16_swap_b32_e32 v128, v129
	v_add_f32_e32 v128, v128, v129
	v_mov_b32_e32 v129, v128
	s_nop 1
	v_permlane32_swap_b32_e32 v128, v129
	s_and_saveexec_b64 s[52:53], s[2:3]
	s_cbranch_execz .LBB0_1240
	v_add_f32_e32 v132, v128, v129
	v_lshrrev_b32_e32 v128, 4, v176
	s_lshl_b32 s64, s6, 2
	v_and_b32_e32 v128, 0xfffffc0, v128
	v_mov_b32_e32 v129, v177
	s_ashr_i32 s65, s64, 31
	v_lshl_add_u64 v[128:129], s[42:43], 0, v[128:129]
	v_lshl_add_u64 v[128:129], s[64:65], 2, v[128:129]
	s_lshl_b32 s44, s80, 2
	v_lshl_add_u64 v[128:129], v[128:129], 0, s[44:45]
	global_store_dword v[128:129], v132, off
